# previous + V tr-reads issued before K-fragment reads (no s_nop 5), ones-constant s_mov hoisted out of the step loop, merge epilogue gate ratios in 8-wide batches
# baseline (speedup 1.0000x reference)
.LBB0_902:
	s_lshl_b32 s0, s73, 2
	s_lshl_b32 s38, s72, 4
	s_add_i32 s0, s0, s71
	s_add_i32 s10, s0, s38
	s_ashr_i32 s11, s10, 31
	s_lshl_b64 s[10:11], s[10:11], 16
	v_lshl_add_u64 v[210:211], v[204:205], 0, s[10:11]
	s_mov_b64 s[10:11], 0x1000
	v_lshl_add_u64 v[212:213], v[210:211], 0, s[10:11]
	s_mov_b64 s[10:11], 0x10000
	v_lshl_add_u64 v[214:215], v[210:211], 0, s[10:11]
	s_mov_b64 s[10:11], 0x11000
	v_lshl_add_u64 v[218:219], v[210:211], 0, s[10:11]
	global_load_dwordx4 v[190:193], v[210:211], off
	global_load_dwordx4 v[182:185], v[210:211], off offset:1024
	global_load_dwordx4 v[174:177], v[210:211], off offset:2048
	global_load_dwordx4 v[166:169], v[210:211], off offset:3072
	global_load_dwordx4 v[158:161], v[212:213], off
	global_load_dwordx4 v[150:153], v[212:213], off offset:1024
	global_load_dwordx4 v[142:145], v[212:213], off offset:2048
	global_load_dwordx4 v[134:137], v[212:213], off offset:3072
	s_cmp_gt_i32 s71, 2
	s_cbranch_scc1 .Lwo_eq3
	global_load_dwordx4 v[194:197], v[214:215], off
	global_load_dwordx4 v[186:189], v[214:215], off offset:1024
	global_load_dwordx4 v[178:181], v[214:215], off offset:2048
	global_load_dwordx4 v[170:173], v[214:215], off offset:3072
	global_load_dwordx4 v[162:165], v[218:219], off
	global_load_dwordx4 v[154:157], v[218:219], off offset:1024
	global_load_dwordx4 v[146:149], v[218:219], off offset:2048
	global_load_dwordx4 v[138:141], v[218:219], off offset:3072
	s_waitcnt vmcnt(0)
	v_cvt_f32_ubyte0_e32 v210, v190
	v_cvt_f32_ubyte1_e32 v211, v190
	v_cvt_f32_ubyte2_e32 v212, v190
	v_cvt_f32_ubyte3_e32 v213, v190
	v_cvt_f32_ubyte0_e32 v228, v191
	v_cvt_f32_ubyte1_e32 v229, v191
	v_cvt_f32_ubyte2_e32 v230, v191
	v_cvt_f32_ubyte3_e32 v231, v191
	v_cvt_f32_ubyte0_e32 v214, v194
	v_cvt_f32_ubyte1_e32 v215, v194
	v_cvt_f32_ubyte2_e32 v218, v194
	v_cvt_f32_ubyte3_e32 v219, v194
	v_cvt_f32_ubyte0_e32 v232, v195
	v_cvt_f32_ubyte1_e32 v233, v195
	v_cvt_f32_ubyte2_e32 v234, v195
	v_cvt_f32_ubyte3_e32 v235, v195
	v_rcp_iflag_f32_e32 v214, v214
	v_rcp_iflag_f32_e32 v215, v215
	v_rcp_iflag_f32_e32 v218, v218
	v_rcp_iflag_f32_e32 v219, v219
	v_rcp_iflag_f32_e32 v232, v232
	v_rcp_iflag_f32_e32 v233, v233
	v_rcp_iflag_f32_e32 v234, v234
	v_rcp_iflag_f32_e32 v235, v235
	v_mul_f32_e32 v210, v214, v210
	v_mul_f32_e32 v211, v215, v211
	v_mul_f32_e32 v212, v218, v212
	v_mul_f32_e32 v213, v219, v213
	v_mul_f32_e32 v228, v232, v228
	v_mul_f32_e32 v229, v233, v229
	v_mul_f32_e32 v230, v234, v230
	v_mul_f32_e32 v231, v235, v231
	v_pk_mul_f32 v[130:131], v[130:131], v[210:211]
	v_pk_mul_f32 v[132:133], v[132:133], v[212:213]
	v_pk_mul_f32 v[126:127], v[126:127], v[228:229]
	v_pk_mul_f32 v[128:129], v[128:129], v[230:231]
	v_cvt_f32_ubyte0_e32 v210, v192
	v_cvt_f32_ubyte1_e32 v211, v192
	v_cvt_f32_ubyte2_e32 v212, v192
	v_cvt_f32_ubyte3_e32 v213, v192
	v_cvt_f32_ubyte0_e32 v228, v193
	v_cvt_f32_ubyte1_e32 v229, v193
	v_cvt_f32_ubyte2_e32 v230, v193
	v_cvt_f32_ubyte3_e32 v231, v193
	v_cvt_f32_ubyte0_e32 v214, v196
	v_cvt_f32_ubyte1_e32 v215, v196
	v_cvt_f32_ubyte2_e32 v218, v196
	v_cvt_f32_ubyte3_e32 v219, v196
	v_cvt_f32_ubyte0_e32 v232, v197
	v_cvt_f32_ubyte1_e32 v233, v197
	v_cvt_f32_ubyte2_e32 v234, v197
	v_cvt_f32_ubyte3_e32 v235, v197
	v_rcp_iflag_f32_e32 v214, v214
	v_rcp_iflag_f32_e32 v215, v215
	v_rcp_iflag_f32_e32 v218, v218
	v_rcp_iflag_f32_e32 v219, v219
	v_rcp_iflag_f32_e32 v232, v232
	v_rcp_iflag_f32_e32 v233, v233
	v_rcp_iflag_f32_e32 v234, v234
	v_rcp_iflag_f32_e32 v235, v235
	v_mul_f32_e32 v210, v214, v210
	v_mul_f32_e32 v211, v215, v211
	v_mul_f32_e32 v212, v218, v212
	v_mul_f32_e32 v213, v219, v213
	v_mul_f32_e32 v228, v232, v228
	v_mul_f32_e32 v229, v233, v229
	v_mul_f32_e32 v230, v234, v230
	v_mul_f32_e32 v231, v235, v231
	v_pk_mul_f32 v[98:99], v[98:99], v[210:211]
	v_pk_mul_f32 v[100:101], v[100:101], v[212:213]
	v_pk_mul_f32 v[94:95], v[94:95], v[228:229]
	v_pk_mul_f32 v[96:97], v[96:97], v[230:231]
	v_cvt_f32_ubyte0_e32 v210, v182
	v_cvt_f32_ubyte1_e32 v211, v182
	v_cvt_f32_ubyte2_e32 v212, v182
	v_cvt_f32_ubyte3_e32 v213, v182
	v_cvt_f32_ubyte0_e32 v228, v183
	v_cvt_f32_ubyte1_e32 v229, v183
	v_cvt_f32_ubyte2_e32 v230, v183
	v_cvt_f32_ubyte3_e32 v231, v183
	v_cvt_f32_ubyte0_e32 v214, v186
	v_cvt_f32_ubyte1_e32 v215, v186
	v_cvt_f32_ubyte2_e32 v218, v186
	v_cvt_f32_ubyte3_e32 v219, v186
	v_cvt_f32_ubyte0_e32 v232, v187
	v_cvt_f32_ubyte1_e32 v233, v187
	v_cvt_f32_ubyte2_e32 v234, v187
	v_cvt_f32_ubyte3_e32 v235, v187
	v_rcp_iflag_f32_e32 v214, v214
	v_rcp_iflag_f32_e32 v215, v215
	v_rcp_iflag_f32_e32 v218, v218
	v_rcp_iflag_f32_e32 v219, v219
	v_rcp_iflag_f32_e32 v232, v232
	v_rcp_iflag_f32_e32 v233, v233
	v_rcp_iflag_f32_e32 v234, v234
	v_rcp_iflag_f32_e32 v235, v235
	v_mul_f32_e32 v210, v214, v210
	v_mul_f32_e32 v211, v215, v211
	v_mul_f32_e32 v212, v218, v212
	v_mul_f32_e32 v213, v219, v213
	v_mul_f32_e32 v228, v232, v228
	v_mul_f32_e32 v229, v233, v229
	v_mul_f32_e32 v230, v234, v230
	v_mul_f32_e32 v231, v235, v231
	v_pk_mul_f32 v[122:123], v[122:123], v[210:211]
	v_pk_mul_f32 v[124:125], v[124:125], v[212:213]
	v_pk_mul_f32 v[118:119], v[118:119], v[228:229]
	v_pk_mul_f32 v[120:121], v[120:121], v[230:231]
	v_cvt_f32_ubyte0_e32 v210, v184
	v_cvt_f32_ubyte1_e32 v211, v184
	v_cvt_f32_ubyte2_e32 v212, v184
	v_cvt_f32_ubyte3_e32 v213, v184
	v_cvt_f32_ubyte0_e32 v228, v185
	v_cvt_f32_ubyte1_e32 v229, v185
	v_cvt_f32_ubyte2_e32 v230, v185
	v_cvt_f32_ubyte3_e32 v231, v185
	v_cvt_f32_ubyte0_e32 v214, v188
	v_cvt_f32_ubyte1_e32 v215, v188
	v_cvt_f32_ubyte2_e32 v218, v188
	v_cvt_f32_ubyte3_e32 v219, v188
	v_cvt_f32_ubyte0_e32 v232, v189
	v_cvt_f32_ubyte1_e32 v233, v189
	v_cvt_f32_ubyte2_e32 v234, v189
	v_cvt_f32_ubyte3_e32 v235, v189
	v_rcp_iflag_f32_e32 v214, v214
	v_rcp_iflag_f32_e32 v215, v215
	v_rcp_iflag_f32_e32 v218, v218
	v_rcp_iflag_f32_e32 v219, v219
	v_rcp_iflag_f32_e32 v232, v232
	v_rcp_iflag_f32_e32 v233, v233
	v_rcp_iflag_f32_e32 v234, v234
	v_rcp_iflag_f32_e32 v235, v235
	v_mul_f32_e32 v210, v214, v210
	v_mul_f32_e32 v211, v215, v211
	v_mul_f32_e32 v212, v218, v212
	v_mul_f32_e32 v213, v219, v213
	v_mul_f32_e32 v228, v232, v228
	v_mul_f32_e32 v229, v233, v229
	v_mul_f32_e32 v230, v234, v230
	v_mul_f32_e32 v231, v235, v231
	v_pk_mul_f32 v[90:91], v[90:91], v[210:211]
	v_pk_mul_f32 v[92:93], v[92:93], v[212:213]
	v_pk_mul_f32 v[86:87], v[86:87], v[228:229]
	v_pk_mul_f32 v[88:89], v[88:89], v[230:231]
	v_cvt_f32_ubyte0_e32 v210, v174
	v_cvt_f32_ubyte1_e32 v211, v174
	v_cvt_f32_ubyte2_e32 v212, v174
	v_cvt_f32_ubyte3_e32 v213, v174
	v_cvt_f32_ubyte0_e32 v228, v175
	v_cvt_f32_ubyte1_e32 v229, v175
	v_cvt_f32_ubyte2_e32 v230, v175
	v_cvt_f32_ubyte3_e32 v231, v175
	v_cvt_f32_ubyte0_e32 v214, v178
	v_cvt_f32_ubyte1_e32 v215, v178
	v_cvt_f32_ubyte2_e32 v218, v178
	v_cvt_f32_ubyte3_e32 v219, v178
	v_cvt_f32_ubyte0_e32 v232, v179
	v_cvt_f32_ubyte1_e32 v233, v179
	v_cvt_f32_ubyte2_e32 v234, v179
	v_cvt_f32_ubyte3_e32 v235, v179
	v_rcp_iflag_f32_e32 v214, v214
	v_rcp_iflag_f32_e32 v215, v215
	v_rcp_iflag_f32_e32 v218, v218
	v_rcp_iflag_f32_e32 v219, v219
	v_rcp_iflag_f32_e32 v232, v232
	v_rcp_iflag_f32_e32 v233, v233
	v_rcp_iflag_f32_e32 v234, v234
	v_rcp_iflag_f32_e32 v235, v235
	v_mul_f32_e32 v210, v214, v210
	v_mul_f32_e32 v211, v215, v211
	v_mul_f32_e32 v212, v218, v212
	v_mul_f32_e32 v213, v219, v213
	v_mul_f32_e32 v228, v232, v228
	v_mul_f32_e32 v229, v233, v229
	v_mul_f32_e32 v230, v234, v230
	v_mul_f32_e32 v231, v235, v231
	v_pk_mul_f32 v[114:115], v[114:115], v[210:211]
	v_pk_mul_f32 v[116:117], v[116:117], v[212:213]
	v_pk_mul_f32 v[110:111], v[110:111], v[228:229]
	v_pk_mul_f32 v[112:113], v[112:113], v[230:231]
	v_cvt_f32_ubyte0_e32 v210, v176
	v_cvt_f32_ubyte1_e32 v211, v176
	v_cvt_f32_ubyte2_e32 v212, v176
	v_cvt_f32_ubyte3_e32 v213, v176
	v_cvt_f32_ubyte0_e32 v228, v177
	v_cvt_f32_ubyte1_e32 v229, v177
	v_cvt_f32_ubyte2_e32 v230, v177
	v_cvt_f32_ubyte3_e32 v231, v177
	v_cvt_f32_ubyte0_e32 v214, v180
	v_cvt_f32_ubyte1_e32 v215, v180
	v_cvt_f32_ubyte2_e32 v218, v180
	v_cvt_f32_ubyte3_e32 v219, v180
	v_cvt_f32_ubyte0_e32 v232, v181
	v_cvt_f32_ubyte1_e32 v233, v181
	v_cvt_f32_ubyte2_e32 v234, v181
	v_cvt_f32_ubyte3_e32 v235, v181
	v_rcp_iflag_f32_e32 v214, v214
	v_rcp_iflag_f32_e32 v215, v215
	v_rcp_iflag_f32_e32 v218, v218
	v_rcp_iflag_f32_e32 v219, v219
	v_rcp_iflag_f32_e32 v232, v232
	v_rcp_iflag_f32_e32 v233, v233
	v_rcp_iflag_f32_e32 v234, v234
	v_rcp_iflag_f32_e32 v235, v235
	v_mul_f32_e32 v210, v214, v210
	v_mul_f32_e32 v211, v215, v211
	v_mul_f32_e32 v212, v218, v212
	v_mul_f32_e32 v213, v219, v213
	v_mul_f32_e32 v228, v232, v228
	v_mul_f32_e32 v229, v233, v229
	v_mul_f32_e32 v230, v234, v230
	v_mul_f32_e32 v231, v235, v231
	v_pk_mul_f32 v[82:83], v[82:83], v[210:211]
	v_pk_mul_f32 v[84:85], v[84:85], v[212:213]
	v_pk_mul_f32 v[78:79], v[78:79], v[228:229]
	v_pk_mul_f32 v[80:81], v[80:81], v[230:231]
	v_cvt_f32_ubyte0_e32 v210, v166
	v_cvt_f32_ubyte1_e32 v211, v166
	v_cvt_f32_ubyte2_e32 v212, v166
	v_cvt_f32_ubyte3_e32 v213, v166
	v_cvt_f32_ubyte0_e32 v228, v167
	v_cvt_f32_ubyte1_e32 v229, v167
	v_cvt_f32_ubyte2_e32 v230, v167
	v_cvt_f32_ubyte3_e32 v231, v167
	v_cvt_f32_ubyte0_e32 v214, v170
	v_cvt_f32_ubyte1_e32 v215, v170
	v_cvt_f32_ubyte2_e32 v218, v170
	v_cvt_f32_ubyte3_e32 v219, v170
	v_cvt_f32_ubyte0_e32 v232, v171
	v_cvt_f32_ubyte1_e32 v233, v171
	v_cvt_f32_ubyte2_e32 v234, v171
	v_cvt_f32_ubyte3_e32 v235, v171
	v_rcp_iflag_f32_e32 v214, v214
	v_rcp_iflag_f32_e32 v215, v215
	v_rcp_iflag_f32_e32 v218, v218
	v_rcp_iflag_f32_e32 v219, v219
	v_rcp_iflag_f32_e32 v232, v232
	v_rcp_iflag_f32_e32 v233, v233
	v_rcp_iflag_f32_e32 v234, v234
	v_rcp_iflag_f32_e32 v235, v235
	v_mul_f32_e32 v210, v214, v210
	v_mul_f32_e32 v211, v215, v211
	v_mul_f32_e32 v212, v218, v212
	v_mul_f32_e32 v213, v219, v213
	v_mul_f32_e32 v228, v232, v228
	v_mul_f32_e32 v229, v233, v229
	v_mul_f32_e32 v230, v234, v230
	v_mul_f32_e32 v231, v235, v231
	v_pk_mul_f32 v[106:107], v[106:107], v[210:211]
	v_pk_mul_f32 v[108:109], v[108:109], v[212:213]
	v_pk_mul_f32 v[102:103], v[102:103], v[228:229]
	v_pk_mul_f32 v[104:105], v[104:105], v[230:231]
	v_cvt_f32_ubyte0_e32 v210, v168
	v_cvt_f32_ubyte1_e32 v211, v168
	v_cvt_f32_ubyte2_e32 v212, v168
	v_cvt_f32_ubyte3_e32 v213, v168
	v_cvt_f32_ubyte0_e32 v228, v169
	v_cvt_f32_ubyte1_e32 v229, v169
	v_cvt_f32_ubyte2_e32 v230, v169
	v_cvt_f32_ubyte3_e32 v231, v169
	v_cvt_f32_ubyte0_e32 v214, v172
	v_cvt_f32_ubyte1_e32 v215, v172
	v_cvt_f32_ubyte2_e32 v218, v172
	v_cvt_f32_ubyte3_e32 v219, v172
	v_cvt_f32_ubyte0_e32 v232, v173
	v_cvt_f32_ubyte1_e32 v233, v173
	v_cvt_f32_ubyte2_e32 v234, v173
	v_cvt_f32_ubyte3_e32 v235, v173
	v_rcp_iflag_f32_e32 v214, v214
	v_rcp_iflag_f32_e32 v215, v215
	v_rcp_iflag_f32_e32 v218, v218
	v_rcp_iflag_f32_e32 v219, v219
	v_rcp_iflag_f32_e32 v232, v232
	v_rcp_iflag_f32_e32 v233, v233
	v_rcp_iflag_f32_e32 v234, v234
	v_rcp_iflag_f32_e32 v235, v235
	v_mul_f32_e32 v210, v214, v210
	v_mul_f32_e32 v211, v215, v211
	v_mul_f32_e32 v212, v218, v212
	v_mul_f32_e32 v213, v219, v213
	v_mul_f32_e32 v228, v232, v228
	v_mul_f32_e32 v229, v233, v229
	v_mul_f32_e32 v230, v234, v230
	v_mul_f32_e32 v231, v235, v231
	v_pk_mul_f32 v[74:75], v[74:75], v[210:211]
	v_pk_mul_f32 v[76:77], v[76:77], v[212:213]
	v_pk_mul_f32 v[70:71], v[70:71], v[228:229]
	v_pk_mul_f32 v[72:73], v[72:73], v[230:231]
	v_cvt_f32_ubyte0_e32 v210, v158
	v_cvt_f32_ubyte1_e32 v211, v158
	v_cvt_f32_ubyte2_e32 v212, v158
	v_cvt_f32_ubyte3_e32 v213, v158
	v_cvt_f32_ubyte0_e32 v228, v159
	v_cvt_f32_ubyte1_e32 v229, v159
	v_cvt_f32_ubyte2_e32 v230, v159
	v_cvt_f32_ubyte3_e32 v231, v159
	v_cvt_f32_ubyte0_e32 v214, v162
	v_cvt_f32_ubyte1_e32 v215, v162
	v_cvt_f32_ubyte2_e32 v218, v162
	v_cvt_f32_ubyte3_e32 v219, v162
	v_cvt_f32_ubyte0_e32 v232, v163
	v_cvt_f32_ubyte1_e32 v233, v163
	v_cvt_f32_ubyte2_e32 v234, v163
	v_cvt_f32_ubyte3_e32 v235, v163
	v_rcp_iflag_f32_e32 v214, v214
	v_rcp_iflag_f32_e32 v215, v215
	v_rcp_iflag_f32_e32 v218, v218
	v_rcp_iflag_f32_e32 v219, v219
	v_rcp_iflag_f32_e32 v232, v232
	v_rcp_iflag_f32_e32 v233, v233
	v_rcp_iflag_f32_e32 v234, v234
	v_rcp_iflag_f32_e32 v235, v235
	v_mul_f32_e32 v210, v214, v210
	v_mul_f32_e32 v211, v215, v211
	v_mul_f32_e32 v212, v218, v212
	v_mul_f32_e32 v213, v219, v213
	v_mul_f32_e32 v228, v232, v228
	v_mul_f32_e32 v229, v233, v229
	v_mul_f32_e32 v230, v234, v230
	v_mul_f32_e32 v231, v235, v231
	v_pk_mul_f32 v[66:67], v[66:67], v[210:211]
	v_pk_mul_f32 v[68:69], v[68:69], v[212:213]
	v_pk_mul_f32 v[62:63], v[62:63], v[228:229]
	v_pk_mul_f32 v[64:65], v[64:65], v[230:231]
	v_cvt_f32_ubyte0_e32 v210, v160
	v_cvt_f32_ubyte1_e32 v211, v160
	v_cvt_f32_ubyte2_e32 v212, v160
	v_cvt_f32_ubyte3_e32 v213, v160
	v_cvt_f32_ubyte0_e32 v228, v161
	v_cvt_f32_ubyte1_e32 v229, v161
	v_cvt_f32_ubyte2_e32 v230, v161
	v_cvt_f32_ubyte3_e32 v231, v161
	v_cvt_f32_ubyte0_e32 v214, v164
	v_cvt_f32_ubyte1_e32 v215, v164
	v_cvt_f32_ubyte2_e32 v218, v164
	v_cvt_f32_ubyte3_e32 v219, v164
	v_cvt_f32_ubyte0_e32 v232, v165
	v_cvt_f32_ubyte1_e32 v233, v165
	v_cvt_f32_ubyte2_e32 v234, v165
	v_cvt_f32_ubyte3_e32 v235, v165
	v_rcp_iflag_f32_e32 v214, v214
	v_rcp_iflag_f32_e32 v215, v215
	v_rcp_iflag_f32_e32 v218, v218
	v_rcp_iflag_f32_e32 v219, v219
	v_rcp_iflag_f32_e32 v232, v232
	v_rcp_iflag_f32_e32 v233, v233
	v_rcp_iflag_f32_e32 v234, v234
	v_rcp_iflag_f32_e32 v235, v235
	v_mul_f32_e32 v210, v214, v210
	v_mul_f32_e32 v211, v215, v211
	v_mul_f32_e32 v212, v218, v212
	v_mul_f32_e32 v213, v219, v213
	v_mul_f32_e32 v228, v232, v228
	v_mul_f32_e32 v229, v233, v229
	v_mul_f32_e32 v230, v234, v230
	v_mul_f32_e32 v231, v235, v231
	v_pk_mul_f32 v[28:29], v[28:29], v[210:211]
	v_pk_mul_f32 v[30:31], v[30:31], v[212:213]
	v_pk_mul_f32 v[24:25], v[24:25], v[228:229]
	v_pk_mul_f32 v[26:27], v[26:27], v[230:231]
	v_cvt_f32_ubyte0_e32 v210, v150
	v_cvt_f32_ubyte1_e32 v211, v150
	v_cvt_f32_ubyte2_e32 v212, v150
	v_cvt_f32_ubyte3_e32 v213, v150
	v_cvt_f32_ubyte0_e32 v228, v151
	v_cvt_f32_ubyte1_e32 v229, v151
	v_cvt_f32_ubyte2_e32 v230, v151
	v_cvt_f32_ubyte3_e32 v231, v151
	v_cvt_f32_ubyte0_e32 v214, v154
	v_cvt_f32_ubyte1_e32 v215, v154
	v_cvt_f32_ubyte2_e32 v218, v154
	v_cvt_f32_ubyte3_e32 v219, v154
	v_cvt_f32_ubyte0_e32 v232, v155
	v_cvt_f32_ubyte1_e32 v233, v155
	v_cvt_f32_ubyte2_e32 v234, v155
	v_cvt_f32_ubyte3_e32 v235, v155
	v_rcp_iflag_f32_e32 v214, v214
	v_rcp_iflag_f32_e32 v215, v215
	v_rcp_iflag_f32_e32 v218, v218
	v_rcp_iflag_f32_e32 v219, v219
	v_rcp_iflag_f32_e32 v232, v232
	v_rcp_iflag_f32_e32 v233, v233
	v_rcp_iflag_f32_e32 v234, v234
	v_rcp_iflag_f32_e32 v235, v235
	v_mul_f32_e32 v210, v214, v210
	v_mul_f32_e32 v211, v215, v211
	v_mul_f32_e32 v212, v218, v212
	v_mul_f32_e32 v213, v219, v213
	v_mul_f32_e32 v228, v232, v228
	v_mul_f32_e32 v229, v233, v229
	v_mul_f32_e32 v230, v234, v230
	v_mul_f32_e32 v231, v235, v231
	v_pk_mul_f32 v[58:59], v[58:59], v[210:211]
	v_pk_mul_f32 v[60:61], v[60:61], v[212:213]
	v_pk_mul_f32 v[54:55], v[54:55], v[228:229]
	v_pk_mul_f32 v[56:57], v[56:57], v[230:231]
	v_cvt_f32_ubyte0_e32 v210, v152
	v_cvt_f32_ubyte1_e32 v211, v152
	v_cvt_f32_ubyte2_e32 v212, v152
	v_cvt_f32_ubyte3_e32 v213, v152
	v_cvt_f32_ubyte0_e32 v228, v153
	v_cvt_f32_ubyte1_e32 v229, v153
	v_cvt_f32_ubyte2_e32 v230, v153
	v_cvt_f32_ubyte3_e32 v231, v153
	v_cvt_f32_ubyte0_e32 v214, v156
	v_cvt_f32_ubyte1_e32 v215, v156
	v_cvt_f32_ubyte2_e32 v218, v156
	v_cvt_f32_ubyte3_e32 v219, v156
	v_cvt_f32_ubyte0_e32 v232, v157
	v_cvt_f32_ubyte1_e32 v233, v157
	v_cvt_f32_ubyte2_e32 v234, v157
	v_cvt_f32_ubyte3_e32 v235, v157
	v_rcp_iflag_f32_e32 v214, v214
	v_rcp_iflag_f32_e32 v215, v215
	v_rcp_iflag_f32_e32 v218, v218
	v_rcp_iflag_f32_e32 v219, v219
	v_rcp_iflag_f32_e32 v232, v232
	v_rcp_iflag_f32_e32 v233, v233
	v_rcp_iflag_f32_e32 v234, v234
	v_rcp_iflag_f32_e32 v235, v235
	v_mul_f32_e32 v210, v214, v210
	v_mul_f32_e32 v211, v215, v211
	v_mul_f32_e32 v212, v218, v212
	v_mul_f32_e32 v213, v219, v213
	v_mul_f32_e32 v228, v232, v228
	v_mul_f32_e32 v229, v233, v229
	v_mul_f32_e32 v230, v234, v230
	v_mul_f32_e32 v231, v235, v231
	v_pk_mul_f32 v[20:21], v[20:21], v[210:211]
	v_pk_mul_f32 v[22:23], v[22:23], v[212:213]
	v_pk_mul_f32 v[16:17], v[16:17], v[228:229]
	v_pk_mul_f32 v[18:19], v[18:19], v[230:231]
	v_cvt_f32_ubyte0_e32 v210, v142
	v_cvt_f32_ubyte1_e32 v211, v142
	v_cvt_f32_ubyte2_e32 v212, v142
	v_cvt_f32_ubyte3_e32 v213, v142
	v_cvt_f32_ubyte0_e32 v228, v143
	v_cvt_f32_ubyte1_e32 v229, v143
	v_cvt_f32_ubyte2_e32 v230, v143
	v_cvt_f32_ubyte3_e32 v231, v143
	v_cvt_f32_ubyte0_e32 v214, v146
	v_cvt_f32_ubyte1_e32 v215, v146
	v_cvt_f32_ubyte2_e32 v218, v146
	v_cvt_f32_ubyte3_e32 v219, v146
	v_cvt_f32_ubyte0_e32 v232, v147
	v_cvt_f32_ubyte1_e32 v233, v147
	v_cvt_f32_ubyte2_e32 v234, v147
	v_cvt_f32_ubyte3_e32 v235, v147
	v_rcp_iflag_f32_e32 v214, v214
	v_rcp_iflag_f32_e32 v215, v215
	v_rcp_iflag_f32_e32 v218, v218
	v_rcp_iflag_f32_e32 v219, v219
	v_rcp_iflag_f32_e32 v232, v232
	v_rcp_iflag_f32_e32 v233, v233
	v_rcp_iflag_f32_e32 v234, v234
	v_rcp_iflag_f32_e32 v235, v235
	v_mul_f32_e32 v210, v214, v210
	v_mul_f32_e32 v211, v215, v211
	v_mul_f32_e32 v212, v218, v212
	v_mul_f32_e32 v213, v219, v213
	v_mul_f32_e32 v228, v232, v228
	v_mul_f32_e32 v229, v233, v229
	v_mul_f32_e32 v230, v234, v230
	v_mul_f32_e32 v231, v235, v231
	v_pk_mul_f32 v[50:51], v[50:51], v[210:211]
	v_pk_mul_f32 v[52:53], v[52:53], v[212:213]
	v_pk_mul_f32 v[46:47], v[46:47], v[228:229]
	v_pk_mul_f32 v[48:49], v[48:49], v[230:231]
	v_cvt_f32_ubyte0_e32 v210, v144
	v_cvt_f32_ubyte1_e32 v211, v144
	v_cvt_f32_ubyte2_e32 v212, v144
	v_cvt_f32_ubyte3_e32 v213, v144
	v_cvt_f32_ubyte0_e32 v228, v145
	v_cvt_f32_ubyte1_e32 v229, v145
	v_cvt_f32_ubyte2_e32 v230, v145
	v_cvt_f32_ubyte3_e32 v231, v145
	v_cvt_f32_ubyte0_e32 v214, v148
	v_cvt_f32_ubyte1_e32 v215, v148
	v_cvt_f32_ubyte2_e32 v218, v148
	v_cvt_f32_ubyte3_e32 v219, v148
	v_cvt_f32_ubyte0_e32 v232, v149
	v_cvt_f32_ubyte1_e32 v233, v149
	v_cvt_f32_ubyte2_e32 v234, v149
	v_cvt_f32_ubyte3_e32 v235, v149
	v_rcp_iflag_f32_e32 v214, v214
	v_rcp_iflag_f32_e32 v215, v215
	v_rcp_iflag_f32_e32 v218, v218
	v_rcp_iflag_f32_e32 v219, v219
	v_rcp_iflag_f32_e32 v232, v232
	v_rcp_iflag_f32_e32 v233, v233
	v_rcp_iflag_f32_e32 v234, v234
	v_rcp_iflag_f32_e32 v235, v235
	v_mul_f32_e32 v210, v214, v210
	v_mul_f32_e32 v211, v215, v211
	v_mul_f32_e32 v212, v218, v212
	v_mul_f32_e32 v213, v219, v213
	v_mul_f32_e32 v228, v232, v228
	v_mul_f32_e32 v229, v233, v229
	v_mul_f32_e32 v230, v234, v230
	v_mul_f32_e32 v231, v235, v231
	v_pk_mul_f32 v[12:13], v[12:13], v[210:211]
	v_pk_mul_f32 v[14:15], v[14:15], v[212:213]
	v_pk_mul_f32 v[8:9], v[8:9], v[228:229]
	v_pk_mul_f32 v[10:11], v[10:11], v[230:231]
	v_cvt_f32_ubyte0_e32 v210, v134
	v_cvt_f32_ubyte1_e32 v211, v134
	v_cvt_f32_ubyte2_e32 v212, v134
	v_cvt_f32_ubyte3_e32 v213, v134
	v_cvt_f32_ubyte0_e32 v228, v135
	v_cvt_f32_ubyte1_e32 v229, v135
	v_cvt_f32_ubyte2_e32 v230, v135
	v_cvt_f32_ubyte3_e32 v231, v135
	v_cvt_f32_ubyte0_e32 v214, v138
	v_cvt_f32_ubyte1_e32 v215, v138
	v_cvt_f32_ubyte2_e32 v218, v138
	v_cvt_f32_ubyte3_e32 v219, v138
	v_cvt_f32_ubyte0_e32 v232, v139
	v_cvt_f32_ubyte1_e32 v233, v139
	v_cvt_f32_ubyte2_e32 v234, v139
	v_cvt_f32_ubyte3_e32 v235, v139
	v_rcp_iflag_f32_e32 v214, v214
	v_rcp_iflag_f32_e32 v215, v215
	v_rcp_iflag_f32_e32 v218, v218
	v_rcp_iflag_f32_e32 v219, v219
	v_rcp_iflag_f32_e32 v232, v232
	v_rcp_iflag_f32_e32 v233, v233
	v_rcp_iflag_f32_e32 v234, v234
	v_rcp_iflag_f32_e32 v235, v235
	v_mul_f32_e32 v210, v214, v210
	v_mul_f32_e32 v211, v215, v211
	v_mul_f32_e32 v212, v218, v212
	v_mul_f32_e32 v213, v219, v213
	v_mul_f32_e32 v228, v232, v228
	v_mul_f32_e32 v229, v233, v229
	v_mul_f32_e32 v230, v234, v230
	v_mul_f32_e32 v231, v235, v231
	v_pk_mul_f32 v[42:43], v[42:43], v[210:211]
	v_pk_mul_f32 v[44:45], v[44:45], v[212:213]
	v_pk_mul_f32 v[38:39], v[38:39], v[228:229]
	v_pk_mul_f32 v[40:41], v[40:41], v[230:231]
	v_cvt_f32_ubyte0_e32 v210, v136
	v_cvt_f32_ubyte1_e32 v211, v136
	v_cvt_f32_ubyte2_e32 v212, v136
	v_cvt_f32_ubyte3_e32 v213, v136
	v_cvt_f32_ubyte0_e32 v228, v137
	v_cvt_f32_ubyte1_e32 v229, v137
	v_cvt_f32_ubyte2_e32 v230, v137
	v_cvt_f32_ubyte3_e32 v231, v137
	v_cvt_f32_ubyte0_e32 v214, v140
	v_cvt_f32_ubyte1_e32 v215, v140
	v_cvt_f32_ubyte2_e32 v218, v140
	v_cvt_f32_ubyte3_e32 v219, v140
	v_cvt_f32_ubyte0_e32 v232, v141
	v_cvt_f32_ubyte1_e32 v233, v141
	v_cvt_f32_ubyte2_e32 v234, v141
	v_cvt_f32_ubyte3_e32 v235, v141
	v_rcp_iflag_f32_e32 v214, v214
	v_rcp_iflag_f32_e32 v215, v215
	v_rcp_iflag_f32_e32 v218, v218
	v_rcp_iflag_f32_e32 v219, v219
	v_rcp_iflag_f32_e32 v232, v232
	v_rcp_iflag_f32_e32 v233, v233
	v_rcp_iflag_f32_e32 v234, v234
	v_rcp_iflag_f32_e32 v235, v235
	v_mul_f32_e32 v210, v214, v210
	v_mul_f32_e32 v211, v215, v211
	v_mul_f32_e32 v212, v218, v212
	v_mul_f32_e32 v213, v219, v213
	v_mul_f32_e32 v228, v232, v228
	v_mul_f32_e32 v229, v233, v229
	v_mul_f32_e32 v230, v234, v230
	v_mul_f32_e32 v231, v235, v231
	v_pk_mul_f32 v[4:5], v[4:5], v[210:211]
	v_pk_mul_f32 v[6:7], v[6:7], v[212:213]
	v_pk_mul_f32 v[0:1], v[0:1], v[228:229]
	v_pk_mul_f32 v[2:3], v[2:3], v[230:231]
	s_branch .LBB0_1465
.Lwo_eq3:
	s_waitcnt vmcnt(0)
	s_lshl_b32 s0, s73, 9
	s_lshl_b32 s12, s72, 19
	s_add_i32 s12, s12, s0
	v_add_u32_e32 v245, s12, v243
	s_mov_b32 s0, 0x0
	v_cvt_f32_ubyte0_e32 v210, v190
	v_cvt_f32_ubyte1_e32 v211, v190
	v_cvt_f32_ubyte2_e32 v212, v190
	v_cvt_f32_ubyte3_e32 v213, v190
	v_cvt_f32_ubyte0_e32 v228, v191
	v_cvt_f32_ubyte1_e32 v229, v191
	v_cvt_f32_ubyte2_e32 v230, v191
	v_cvt_f32_ubyte3_e32 v231, v191
	v_mul_f32_e32 v210, 0x3b800000, v210
	v_mul_f32_e32 v211, 0x3b800000, v211
	v_mul_f32_e32 v212, 0x3b800000, v212
	v_mul_f32_e32 v213, 0x3b800000, v213
	v_mul_f32_e32 v228, 0x3b800000, v228
	v_mul_f32_e32 v229, 0x3b800000, v229
	v_mul_f32_e32 v230, 0x3b800000, v230
	v_mul_f32_e32 v231, 0x3b800000, v231
	v_pk_mul_f32 v[130:131], v[130:131], v[210:211]
	v_pk_mul_f32 v[132:133], v[132:133], v[212:213]
	v_pk_mul_f32 v[126:127], v[126:127], v[228:229]
	v_pk_mul_f32 v[128:129], v[128:129], v[230:231]
	v_cvt_pk_bf16_f32 v218, v130, v131
	v_cvt_pk_bf16_f32 v219, v132, v133
	v_cvt_pk_bf16_f32 v220, v126, v127
	v_cvt_pk_bf16_f32 v221, v128, v129
	buffer_store_dwordx4 v[218:221], v245, s[48:51], s0 offen sc1
	v_cvt_f32_ubyte0_e32 v210, v192
	v_cvt_f32_ubyte1_e32 v211, v192
	v_cvt_f32_ubyte2_e32 v212, v192
	v_cvt_f32_ubyte3_e32 v213, v192
	v_cvt_f32_ubyte0_e32 v228, v193
	v_cvt_f32_ubyte1_e32 v229, v193
	v_cvt_f32_ubyte2_e32 v230, v193
	v_cvt_f32_ubyte3_e32 v231, v193
	v_mul_f32_e32 v210, 0x3b800000, v210
	v_mul_f32_e32 v211, 0x3b800000, v211
	v_mul_f32_e32 v212, 0x3b800000, v212
	v_mul_f32_e32 v213, 0x3b800000, v213
	v_mul_f32_e32 v228, 0x3b800000, v228
	v_mul_f32_e32 v229, 0x3b800000, v229
	v_mul_f32_e32 v230, 0x3b800000, v230
	v_mul_f32_e32 v231, 0x3b800000, v231
	v_pk_mul_f32 v[98:99], v[98:99], v[210:211]
	v_pk_mul_f32 v[100:101], v[100:101], v[212:213]
	v_pk_mul_f32 v[94:95], v[94:95], v[228:229]
	v_pk_mul_f32 v[96:97], v[96:97], v[230:231]
	v_cvt_pk_bf16_f32 v218, v98, v99
	v_cvt_pk_bf16_f32 v219, v100, v101
	v_cvt_pk_bf16_f32 v220, v94, v95
	v_cvt_pk_bf16_f32 v221, v96, v97
	buffer_store_dwordx4 v[218:221], v245, s[48:51], s0 offen offset:256 sc1
	s_mov_b32 s0, 0x8000
	v_cvt_f32_ubyte0_e32 v210, v182
	v_cvt_f32_ubyte1_e32 v211, v182
	v_cvt_f32_ubyte2_e32 v212, v182
	v_cvt_f32_ubyte3_e32 v213, v182
	v_cvt_f32_ubyte0_e32 v228, v183
	v_cvt_f32_ubyte1_e32 v229, v183
	v_cvt_f32_ubyte2_e32 v230, v183
	v_cvt_f32_ubyte3_e32 v231, v183
	v_mul_f32_e32 v210, 0x3b800000, v210
	v_mul_f32_e32 v211, 0x3b800000, v211
	v_mul_f32_e32 v212, 0x3b800000, v212
	v_mul_f32_e32 v213, 0x3b800000, v213
	v_mul_f32_e32 v228, 0x3b800000, v228
	v_mul_f32_e32 v229, 0x3b800000, v229
	v_mul_f32_e32 v230, 0x3b800000, v230
	v_mul_f32_e32 v231, 0x3b800000, v231
	v_pk_mul_f32 v[122:123], v[122:123], v[210:211]
	v_pk_mul_f32 v[124:125], v[124:125], v[212:213]
	v_pk_mul_f32 v[118:119], v[118:119], v[228:229]
	v_pk_mul_f32 v[120:121], v[120:121], v[230:231]
	v_cvt_pk_bf16_f32 v218, v122, v123
	v_cvt_pk_bf16_f32 v219, v124, v125
	v_cvt_pk_bf16_f32 v220, v118, v119
	v_cvt_pk_bf16_f32 v221, v120, v121
	buffer_store_dwordx4 v[218:221], v245, s[48:51], s0 offen sc1
	v_cvt_f32_ubyte0_e32 v210, v184
	v_cvt_f32_ubyte1_e32 v211, v184
	v_cvt_f32_ubyte2_e32 v212, v184
	v_cvt_f32_ubyte3_e32 v213, v184
	v_cvt_f32_ubyte0_e32 v228, v185
	v_cvt_f32_ubyte1_e32 v229, v185
	v_cvt_f32_ubyte2_e32 v230, v185
	v_cvt_f32_ubyte3_e32 v231, v185
	v_mul_f32_e32 v210, 0x3b800000, v210
	v_mul_f32_e32 v211, 0x3b800000, v211
	v_mul_f32_e32 v212, 0x3b800000, v212
	v_mul_f32_e32 v213, 0x3b800000, v213
	v_mul_f32_e32 v228, 0x3b800000, v228
	v_mul_f32_e32 v229, 0x3b800000, v229
	v_mul_f32_e32 v230, 0x3b800000, v230
	v_mul_f32_e32 v231, 0x3b800000, v231
	v_pk_mul_f32 v[90:91], v[90:91], v[210:211]
	v_pk_mul_f32 v[92:93], v[92:93], v[212:213]
	v_pk_mul_f32 v[86:87], v[86:87], v[228:229]
	v_pk_mul_f32 v[88:89], v[88:89], v[230:231]
	v_cvt_pk_bf16_f32 v218, v90, v91
	v_cvt_pk_bf16_f32 v219, v92, v93
	v_cvt_pk_bf16_f32 v220, v86, v87
	v_cvt_pk_bf16_f32 v221, v88, v89
	buffer_store_dwordx4 v[218:221], v245, s[48:51], s0 offen offset:256 sc1
	s_mov_b32 s0, 0x10000
	v_cvt_f32_ubyte0_e32 v210, v174
	v_cvt_f32_ubyte1_e32 v211, v174
	v_cvt_f32_ubyte2_e32 v212, v174
	v_cvt_f32_ubyte3_e32 v213, v174
	v_cvt_f32_ubyte0_e32 v228, v175
	v_cvt_f32_ubyte1_e32 v229, v175
	v_cvt_f32_ubyte2_e32 v230, v175
	v_cvt_f32_ubyte3_e32 v231, v175
	v_mul_f32_e32 v210, 0x3b800000, v210
	v_mul_f32_e32 v211, 0x3b800000, v211
	v_mul_f32_e32 v212, 0x3b800000, v212
	v_mul_f32_e32 v213, 0x3b800000, v213
	v_mul_f32_e32 v228, 0x3b800000, v228
	v_mul_f32_e32 v229, 0x3b800000, v229
	v_mul_f32_e32 v230, 0x3b800000, v230
	v_mul_f32_e32 v231, 0x3b800000, v231
	v_pk_mul_f32 v[114:115], v[114:115], v[210:211]
	v_pk_mul_f32 v[116:117], v[116:117], v[212:213]
	v_pk_mul_f32 v[110:111], v[110:111], v[228:229]
	v_pk_mul_f32 v[112:113], v[112:113], v[230:231]
	v_cvt_pk_bf16_f32 v218, v114, v115
	v_cvt_pk_bf16_f32 v219, v116, v117
	v_cvt_pk_bf16_f32 v220, v110, v111
	v_cvt_pk_bf16_f32 v221, v112, v113
	buffer_store_dwordx4 v[218:221], v245, s[48:51], s0 offen sc1
	v_cvt_f32_ubyte0_e32 v210, v176
	v_cvt_f32_ubyte1_e32 v211, v176
	v_cvt_f32_ubyte2_e32 v212, v176
	v_cvt_f32_ubyte3_e32 v213, v176
	v_cvt_f32_ubyte0_e32 v228, v177
	v_cvt_f32_ubyte1_e32 v229, v177
	v_cvt_f32_ubyte2_e32 v230, v177
	v_cvt_f32_ubyte3_e32 v231, v177
	v_mul_f32_e32 v210, 0x3b800000, v210
	v_mul_f32_e32 v211, 0x3b800000, v211
	v_mul_f32_e32 v212, 0x3b800000, v212
	v_mul_f32_e32 v213, 0x3b800000, v213
	v_mul_f32_e32 v228, 0x3b800000, v228
	v_mul_f32_e32 v229, 0x3b800000, v229
	v_mul_f32_e32 v230, 0x3b800000, v230
	v_mul_f32_e32 v231, 0x3b800000, v231
	v_pk_mul_f32 v[82:83], v[82:83], v[210:211]
	v_pk_mul_f32 v[84:85], v[84:85], v[212:213]
	v_pk_mul_f32 v[78:79], v[78:79], v[228:229]
	v_pk_mul_f32 v[80:81], v[80:81], v[230:231]
	v_cvt_pk_bf16_f32 v218, v82, v83
	v_cvt_pk_bf16_f32 v219, v84, v85
	v_cvt_pk_bf16_f32 v220, v78, v79
	v_cvt_pk_bf16_f32 v221, v80, v81
	buffer_store_dwordx4 v[218:221], v245, s[48:51], s0 offen offset:256 sc1
	s_mov_b32 s0, 0x18000
	v_cvt_f32_ubyte0_e32 v210, v166
	v_cvt_f32_ubyte1_e32 v211, v166
	v_cvt_f32_ubyte2_e32 v212, v166
	v_cvt_f32_ubyte3_e32 v213, v166
	v_cvt_f32_ubyte0_e32 v228, v167
	v_cvt_f32_ubyte1_e32 v229, v167
	v_cvt_f32_ubyte2_e32 v230, v167
	v_cvt_f32_ubyte3_e32 v231, v167
	v_mul_f32_e32 v210, 0x3b800000, v210
	v_mul_f32_e32 v211, 0x3b800000, v211
	v_mul_f32_e32 v212, 0x3b800000, v212
	v_mul_f32_e32 v213, 0x3b800000, v213
	v_mul_f32_e32 v228, 0x3b800000, v228
	v_mul_f32_e32 v229, 0x3b800000, v229
	v_mul_f32_e32 v230, 0x3b800000, v230
	v_mul_f32_e32 v231, 0x3b800000, v231
	v_pk_mul_f32 v[106:107], v[106:107], v[210:211]
	v_pk_mul_f32 v[108:109], v[108:109], v[212:213]
	v_pk_mul_f32 v[102:103], v[102:103], v[228:229]
	v_pk_mul_f32 v[104:105], v[104:105], v[230:231]
	v_cvt_pk_bf16_f32 v218, v106, v107
	v_cvt_pk_bf16_f32 v219, v108, v109
	v_cvt_pk_bf16_f32 v220, v102, v103
	v_cvt_pk_bf16_f32 v221, v104, v105
	buffer_store_dwordx4 v[218:221], v245, s[48:51], s0 offen sc1
	v_cvt_f32_ubyte0_e32 v210, v168
	v_cvt_f32_ubyte1_e32 v211, v168
	v_cvt_f32_ubyte2_e32 v212, v168
	v_cvt_f32_ubyte3_e32 v213, v168
	v_cvt_f32_ubyte0_e32 v228, v169
	v_cvt_f32_ubyte1_e32 v229, v169
	v_cvt_f32_ubyte2_e32 v230, v169
	v_cvt_f32_ubyte3_e32 v231, v169
	v_mul_f32_e32 v210, 0x3b800000, v210
	v_mul_f32_e32 v211, 0x3b800000, v211
	v_mul_f32_e32 v212, 0x3b800000, v212
	v_mul_f32_e32 v213, 0x3b800000, v213
	v_mul_f32_e32 v228, 0x3b800000, v228
	v_mul_f32_e32 v229, 0x3b800000, v229
	v_mul_f32_e32 v230, 0x3b800000, v230
	v_mul_f32_e32 v231, 0x3b800000, v231
	v_pk_mul_f32 v[74:75], v[74:75], v[210:211]
	v_pk_mul_f32 v[76:77], v[76:77], v[212:213]
	v_pk_mul_f32 v[70:71], v[70:71], v[228:229]
	v_pk_mul_f32 v[72:73], v[72:73], v[230:231]
	v_cvt_pk_bf16_f32 v218, v74, v75
	v_cvt_pk_bf16_f32 v219, v76, v77
	v_cvt_pk_bf16_f32 v220, v70, v71
	v_cvt_pk_bf16_f32 v221, v72, v73
	buffer_store_dwordx4 v[218:221], v245, s[48:51], s0 offen offset:256 sc1
	s_mov_b32 s0, 0x40000
	v_cvt_f32_ubyte0_e32 v210, v158
	v_cvt_f32_ubyte1_e32 v211, v158
	v_cvt_f32_ubyte2_e32 v212, v158
	v_cvt_f32_ubyte3_e32 v213, v158
	v_cvt_f32_ubyte0_e32 v228, v159
	v_cvt_f32_ubyte1_e32 v229, v159
	v_cvt_f32_ubyte2_e32 v230, v159
	v_cvt_f32_ubyte3_e32 v231, v159
	v_mul_f32_e32 v210, 0x3b800000, v210
	v_mul_f32_e32 v211, 0x3b800000, v211
	v_mul_f32_e32 v212, 0x3b800000, v212
	v_mul_f32_e32 v213, 0x3b800000, v213
	v_mul_f32_e32 v228, 0x3b800000, v228
	v_mul_f32_e32 v229, 0x3b800000, v229
	v_mul_f32_e32 v230, 0x3b800000, v230
	v_mul_f32_e32 v231, 0x3b800000, v231
	v_pk_mul_f32 v[66:67], v[66:67], v[210:211]
	v_pk_mul_f32 v[68:69], v[68:69], v[212:213]
	v_pk_mul_f32 v[62:63], v[62:63], v[228:229]
	v_pk_mul_f32 v[64:65], v[64:65], v[230:231]
	v_cvt_pk_bf16_f32 v218, v66, v67
	v_cvt_pk_bf16_f32 v219, v68, v69
	v_cvt_pk_bf16_f32 v220, v62, v63
	v_cvt_pk_bf16_f32 v221, v64, v65
	buffer_store_dwordx4 v[218:221], v245, s[48:51], s0 offen sc1
	v_cvt_f32_ubyte0_e32 v210, v160
	v_cvt_f32_ubyte1_e32 v211, v160
	v_cvt_f32_ubyte2_e32 v212, v160
	v_cvt_f32_ubyte3_e32 v213, v160
	v_cvt_f32_ubyte0_e32 v228, v161
	v_cvt_f32_ubyte1_e32 v229, v161
	v_cvt_f32_ubyte2_e32 v230, v161
	v_cvt_f32_ubyte3_e32 v231, v161
	v_mul_f32_e32 v210, 0x3b800000, v210
	v_mul_f32_e32 v211, 0x3b800000, v211
	v_mul_f32_e32 v212, 0x3b800000, v212
	v_mul_f32_e32 v213, 0x3b800000, v213
	v_mul_f32_e32 v228, 0x3b800000, v228
	v_mul_f32_e32 v229, 0x3b800000, v229
	v_mul_f32_e32 v230, 0x3b800000, v230
	v_mul_f32_e32 v231, 0x3b800000, v231
	v_pk_mul_f32 v[28:29], v[28:29], v[210:211]
	v_pk_mul_f32 v[30:31], v[30:31], v[212:213]
	v_pk_mul_f32 v[24:25], v[24:25], v[228:229]
	v_pk_mul_f32 v[26:27], v[26:27], v[230:231]
	v_cvt_pk_bf16_f32 v218, v28, v29
	v_cvt_pk_bf16_f32 v219, v30, v31
	v_cvt_pk_bf16_f32 v220, v24, v25
	v_cvt_pk_bf16_f32 v221, v26, v27
	buffer_store_dwordx4 v[218:221], v245, s[48:51], s0 offen offset:256 sc1
	s_mov_b32 s0, 0x48000
	v_cvt_f32_ubyte0_e32 v210, v150
	v_cvt_f32_ubyte1_e32 v211, v150
	v_cvt_f32_ubyte2_e32 v212, v150
	v_cvt_f32_ubyte3_e32 v213, v150
	v_cvt_f32_ubyte0_e32 v228, v151
	v_cvt_f32_ubyte1_e32 v229, v151
	v_cvt_f32_ubyte2_e32 v230, v151
	v_cvt_f32_ubyte3_e32 v231, v151
	v_mul_f32_e32 v210, 0x3b800000, v210
	v_mul_f32_e32 v211, 0x3b800000, v211
	v_mul_f32_e32 v212, 0x3b800000, v212
	v_mul_f32_e32 v213, 0x3b800000, v213
	v_mul_f32_e32 v228, 0x3b800000, v228
	v_mul_f32_e32 v229, 0x3b800000, v229
	v_mul_f32_e32 v230, 0x3b800000, v230
	v_mul_f32_e32 v231, 0x3b800000, v231
	v_pk_mul_f32 v[58:59], v[58:59], v[210:211]
	v_pk_mul_f32 v[60:61], v[60:61], v[212:213]
	v_pk_mul_f32 v[54:55], v[54:55], v[228:229]
	v_pk_mul_f32 v[56:57], v[56:57], v[230:231]
	v_cvt_pk_bf16_f32 v218, v58, v59
	v_cvt_pk_bf16_f32 v219, v60, v61
	v_cvt_pk_bf16_f32 v220, v54, v55
	v_cvt_pk_bf16_f32 v221, v56, v57
	buffer_store_dwordx4 v[218:221], v245, s[48:51], s0 offen sc1
	v_cvt_f32_ubyte0_e32 v210, v152
	v_cvt_f32_ubyte1_e32 v211, v152
	v_cvt_f32_ubyte2_e32 v212, v152
	v_cvt_f32_ubyte3_e32 v213, v152
	v_cvt_f32_ubyte0_e32 v228, v153
	v_cvt_f32_ubyte1_e32 v229, v153
	v_cvt_f32_ubyte2_e32 v230, v153
	v_cvt_f32_ubyte3_e32 v231, v153
	v_mul_f32_e32 v210, 0x3b800000, v210
	v_mul_f32_e32 v211, 0x3b800000, v211
	v_mul_f32_e32 v212, 0x3b800000, v212
	v_mul_f32_e32 v213, 0x3b800000, v213
	v_mul_f32_e32 v228, 0x3b800000, v228
	v_mul_f32_e32 v229, 0x3b800000, v229
	v_mul_f32_e32 v230, 0x3b800000, v230
	v_mul_f32_e32 v231, 0x3b800000, v231
	v_pk_mul_f32 v[20:21], v[20:21], v[210:211]
	v_pk_mul_f32 v[22:23], v[22:23], v[212:213]
	v_pk_mul_f32 v[16:17], v[16:17], v[228:229]
	v_pk_mul_f32 v[18:19], v[18:19], v[230:231]
	v_cvt_pk_bf16_f32 v218, v20, v21
	v_cvt_pk_bf16_f32 v219, v22, v23
	v_cvt_pk_bf16_f32 v220, v16, v17
	v_cvt_pk_bf16_f32 v221, v18, v19
	buffer_store_dwordx4 v[218:221], v245, s[48:51], s0 offen offset:256 sc1
	s_mov_b32 s0, 0x50000
	v_cvt_f32_ubyte0_e32 v210, v142
	v_cvt_f32_ubyte1_e32 v211, v142
	v_cvt_f32_ubyte2_e32 v212, v142
	v_cvt_f32_ubyte3_e32 v213, v142
	v_cvt_f32_ubyte0_e32 v228, v143
	v_cvt_f32_ubyte1_e32 v229, v143
	v_cvt_f32_ubyte2_e32 v230, v143
	v_cvt_f32_ubyte3_e32 v231, v143
	v_mul_f32_e32 v210, 0x3b800000, v210
	v_mul_f32_e32 v211, 0x3b800000, v211
	v_mul_f32_e32 v212, 0x3b800000, v212
	v_mul_f32_e32 v213, 0x3b800000, v213
	v_mul_f32_e32 v228, 0x3b800000, v228
	v_mul_f32_e32 v229, 0x3b800000, v229
	v_mul_f32_e32 v230, 0x3b800000, v230
	v_mul_f32_e32 v231, 0x3b800000, v231
	v_pk_mul_f32 v[50:51], v[50:51], v[210:211]
	v_pk_mul_f32 v[52:53], v[52:53], v[212:213]
	v_pk_mul_f32 v[46:47], v[46:47], v[228:229]
	v_pk_mul_f32 v[48:49], v[48:49], v[230:231]
	v_cvt_pk_bf16_f32 v218, v50, v51
	v_cvt_pk_bf16_f32 v219, v52, v53
	v_cvt_pk_bf16_f32 v220, v46, v47
	v_cvt_pk_bf16_f32 v221, v48, v49
	buffer_store_dwordx4 v[218:221], v245, s[48:51], s0 offen sc1
	v_cvt_f32_ubyte0_e32 v210, v144
	v_cvt_f32_ubyte1_e32 v211, v144
	v_cvt_f32_ubyte2_e32 v212, v144
	v_cvt_f32_ubyte3_e32 v213, v144
	v_cvt_f32_ubyte0_e32 v228, v145
	v_cvt_f32_ubyte1_e32 v229, v145
	v_cvt_f32_ubyte2_e32 v230, v145
	v_cvt_f32_ubyte3_e32 v231, v145
	v_mul_f32_e32 v210, 0x3b800000, v210
	v_mul_f32_e32 v211, 0x3b800000, v211
	v_mul_f32_e32 v212, 0x3b800000, v212
	v_mul_f32_e32 v213, 0x3b800000, v213
	v_mul_f32_e32 v228, 0x3b800000, v228
	v_mul_f32_e32 v229, 0x3b800000, v229
	v_mul_f32_e32 v230, 0x3b800000, v230
	v_mul_f32_e32 v231, 0x3b800000, v231
	v_pk_mul_f32 v[12:13], v[12:13], v[210:211]
	v_pk_mul_f32 v[14:15], v[14:15], v[212:213]
	v_pk_mul_f32 v[8:9], v[8:9], v[228:229]
	v_pk_mul_f32 v[10:11], v[10:11], v[230:231]
	v_cvt_pk_bf16_f32 v218, v12, v13
	v_cvt_pk_bf16_f32 v219, v14, v15
	v_cvt_pk_bf16_f32 v220, v8, v9
	v_cvt_pk_bf16_f32 v221, v10, v11
	buffer_store_dwordx4 v[218:221], v245, s[48:51], s0 offen offset:256 sc1
	s_mov_b32 s0, 0x58000
	v_cvt_f32_ubyte0_e32 v210, v134
	v_cvt_f32_ubyte1_e32 v211, v134
	v_cvt_f32_ubyte2_e32 v212, v134
	v_cvt_f32_ubyte3_e32 v213, v134
	v_cvt_f32_ubyte0_e32 v228, v135
	v_cvt_f32_ubyte1_e32 v229, v135
	v_cvt_f32_ubyte2_e32 v230, v135
	v_cvt_f32_ubyte3_e32 v231, v135
	v_mul_f32_e32 v210, 0x3b800000, v210
	v_mul_f32_e32 v211, 0x3b800000, v211
	v_mul_f32_e32 v212, 0x3b800000, v212
	v_mul_f32_e32 v213, 0x3b800000, v213
	v_mul_f32_e32 v228, 0x3b800000, v228
	v_mul_f32_e32 v229, 0x3b800000, v229
	v_mul_f32_e32 v230, 0x3b800000, v230
	v_mul_f32_e32 v231, 0x3b800000, v231
	v_pk_mul_f32 v[42:43], v[42:43], v[210:211]
	v_pk_mul_f32 v[44:45], v[44:45], v[212:213]
	v_pk_mul_f32 v[38:39], v[38:39], v[228:229]
	v_pk_mul_f32 v[40:41], v[40:41], v[230:231]
	v_cvt_pk_bf16_f32 v218, v42, v43
	v_cvt_pk_bf16_f32 v219, v44, v45
	v_cvt_pk_bf16_f32 v220, v38, v39
	v_cvt_pk_bf16_f32 v221, v40, v41
	buffer_store_dwordx4 v[218:221], v245, s[48:51], s0 offen sc1
	v_cvt_f32_ubyte0_e32 v210, v136
	v_cvt_f32_ubyte1_e32 v211, v136
	v_cvt_f32_ubyte2_e32 v212, v136
	v_cvt_f32_ubyte3_e32 v213, v136
	v_cvt_f32_ubyte0_e32 v228, v137
	v_cvt_f32_ubyte1_e32 v229, v137
	v_cvt_f32_ubyte2_e32 v230, v137
	v_cvt_f32_ubyte3_e32 v231, v137
	v_mul_f32_e32 v210, 0x3b800000, v210
	v_mul_f32_e32 v211, 0x3b800000, v211
	v_mul_f32_e32 v212, 0x3b800000, v212
	v_mul_f32_e32 v213, 0x3b800000, v213
	v_mul_f32_e32 v228, 0x3b800000, v228
	v_mul_f32_e32 v229, 0x3b800000, v229
	v_mul_f32_e32 v230, 0x3b800000, v230
	v_mul_f32_e32 v231, 0x3b800000, v231
	v_pk_mul_f32 v[4:5], v[4:5], v[210:211]
	v_pk_mul_f32 v[6:7], v[6:7], v[212:213]
	v_pk_mul_f32 v[0:1], v[0:1], v[228:229]
	v_pk_mul_f32 v[2:3], v[2:3], v[230:231]
	v_cvt_pk_bf16_f32 v218, v4, v5
	v_cvt_pk_bf16_f32 v219, v6, v7
	v_cvt_pk_bf16_f32 v220, v0, v1
	v_cvt_pk_bf16_f32 v221, v2, v3
	buffer_store_dwordx4 v[218:221], v245, s[48:51], s0 offen offset:256 sc1
	s_waitcnt vmcnt(0)
	v_cmp_eq_u32_e32 vcc, 0, v242
	s_and_saveexec_b64 s[12:13], vcc
	s_cbranch_execz .LBB0_1464
	s_mov_b64 s[34:35], exec
	v_mbcnt_lo_u32_b32 v134, s34, 0
	v_mbcnt_hi_u32_b32 v134, s35, v134
	v_cmp_eq_u32_e32 vcc, 0, v134
	s_and_b64 s[72:73], exec, vcc
	s_mov_b64 exec, s[72:73]
	s_cbranch_execz .LBB0_1464
	s_ashr_i32 s39, s38, 31
	s_lshl_b64 s[38:39], s[38:39], 2
	s_add_u32 s38, s55, s38
	s_addc_u32 s39, s56, s39
	s_bcnt1_i32_b64 s0, s[34:35]
	v_mov_b32_e32 v134, s0
	global_atomic_add v33, v134, s[38:39]
